# grid barrier: all workgroups poll the cross-XCD arrival counter directly, XCD leader adds without return; drops two release hops
# baseline (speedup 1.0000x reference)
.LBB0_131:
	s_lshl_b32 s0, s36, 8
	s_add_u32 s0, s34, s0
	s_addc_u32 s1, s35, 0
	v_mov_b32_e32 v1, s0
	v_add_co_u32_e32 v4, vcc, 0x601000, v1
	v_mov_b32_e32 v1, s1
	s_nop 0
	v_addc_co_u32_e32 v5, vcc, 0, v1, vcc
	v_mov_b32_e32 v1, 1
	flat_atomic_add v1, v[4:5], v1 offset:1024 sc0
	v_cvt_f32_u32_e32 v3, v2
	v_sub_u32_e32 v4, 0, v2
	s_add_u32 s23, s0, 0x600000
	s_addc_u32 s22, s1, 0
	v_rcp_iflag_f32_e32 v3, v3
	s_nop 0
	v_mul_f32_e32 v3, 0x4f7ffffe, v3
	v_cvt_u32_f32_e32 v3, v3
	v_mul_lo_u32 v4, v4, v3
	v_mul_hi_u32 v4, v3, v4
	v_add_u32_e32 v3, v3, v4
	s_waitcnt vmcnt(0) lgkmcnt(0)
	v_mul_hi_u32 v3, v1, v3
	v_mul_lo_u32 v5, v3, v2
	v_add_u32_e32 v4, 1, v1
	v_sub_u32_e32 v1, v1, v5
	v_add_u32_e32 v6, 1, v3
	v_cmp_ge_u32_e32 vcc, v1, v2
	v_sub_u32_e32 v5, v1, v2
	s_nop 0
	v_cndmask_b32_e32 v3, v3, v6, vcc
	v_cndmask_b32_e32 v1, v1, v5, vcc
	v_add_u32_e32 v5, 1, v3
	v_cmp_ge_u32_e32 vcc, v1, v2
	s_nop 1
	v_cndmask_b32_e32 v1, v3, v5, vcc
	v_mad_u64_u32 v[2:3], s[0:1], v2, v1, v[2:3]
	s_add_u32 s6, s34, 0x603400
	s_addc_u32 s7, s35, 0
	v_cmp_eq_u32_e32 vcc, v4, v2
	v_mov_b64_e32 v[2:3], s[6:7]
	v_mov_b32_e32 v4, 1
	s_cbranch_vccz .Lgs_nl_0
	buffer_wbl2 sc1
	s_waitcnt vmcnt(0)
	flat_atomic_add v[2:3], v4
.Lgs_nl_0:
	s_mov_b64 vcc, exec
	s_and_saveexec_b64 s[0:1], vcc
	s_xor_b64 s[0:1], exec, s[0:1]
	s_cbranch_execz .LBB0_144
	v_add_u32_e32 v1, 1, v1
	v_mul_lo_u32 v1, v1, v0
	flat_load_dword v0, v[2:3] sc1
	s_waitcnt vmcnt(0) lgkmcnt(0)
	v_cmp_lt_u32_e32 vcc, v0, v1
	s_and_saveexec_b64 s[2:3], vcc
	s_cbranch_execz .LBB0_143
	s_add_u32 s4, s34, 0x600200
	s_addc_u32 s5, s35, 0
	s_mov_b32 s24, 1
	s_mov_b64 s[8:9], 0
	s_branch .LBB0_135

.LBB0_139:
	s_andn2_b64 s[12:13], s[12:13], exec
	s_and_b64 s[18:19], s[18:19], exec
	s_or_b64 s[12:13], s[12:13], s[18:19]
	s_and_saveexec_b64 s[18:19], s[16:17]
	s_cbranch_execz .LBB0_134
	v_mov_b64_e32 v[2:3], s[6:7]
	flat_load_dword v0, v[2:3] sc1
	s_add_i32 s24, s24, 1
	s_or_b64 s[12:13], s[12:13], exec
	s_waitcnt vmcnt(0) lgkmcnt(0)
	v_cmp_ge_u32_e32 vcc, v0, v1
	s_orn2_b64 s[14:15], vcc, exec
	s_branch .LBB0_134

.LBB0_276:
	s_lshl_b32 s0, s63, 8
	s_add_u32 s0, s44, s0
	s_addc_u32 s1, s62, 0
	v_mov_b32_e32 v1, s0
	v_add_co_u32_e32 v4, vcc, 0x601000, v1
	v_mov_b32_e32 v1, s1
	s_nop 0
	v_addc_co_u32_e32 v5, vcc, 0, v1, vcc
	flat_atomic_add v3, v[4:5], v219 offset:1024 sc0
	v_cvt_f32_u32_e32 v1, v2
	v_sub_u32_e32 v4, 0, v2
	s_add_u32 s23, s0, 0x600000
	s_addc_u32 s22, s1, 0
	v_rcp_iflag_f32_e32 v1, v1
	s_nop 0
	v_mul_f32_e32 v1, 0x4f7ffffe, v1
	v_cvt_u32_f32_e32 v1, v1
	v_mul_lo_u32 v4, v4, v1
	v_mul_hi_u32 v4, v1, v4
	v_add_u32_e32 v1, v1, v4
	s_waitcnt vmcnt(0) lgkmcnt(0)
	v_mul_hi_u32 v1, v3, v1
	v_mul_lo_u32 v4, v1, v2
	v_sub_u32_e32 v4, v3, v4
	v_cmp_ge_u32_e32 vcc, v4, v2
	v_add_u32_e32 v5, 1, v1
	s_nop 0
	v_cndmask_b32_e32 v1, v1, v5, vcc
	v_sub_u32_e32 v5, v4, v2
	v_cndmask_b32_e32 v4, v4, v5, vcc
	v_cmp_ge_u32_e32 vcc, v4, v2
	v_add_u32_e32 v4, 1, v1
	s_nop 0
	v_cndmask_b32_e32 v1, v1, v4, vcc
	v_add_u32_e32 v4, 1, v3
	v_mad_u64_u32 v[2:3], s[0:1], v2, v1, v[2:3]
	s_add_u32 s4, s44, 0x603400
	s_addc_u32 s5, s62, 0
	v_cmp_eq_u32_e32 vcc, v4, v2
	v_mov_b64_e32 v[2:3], s[4:5]
	v_mov_b32_e32 v4, 1
	s_cbranch_vccz .Lgs_nl_2
	buffer_wbl2 sc1
	s_waitcnt vmcnt(0)
	flat_atomic_add v[2:3], v4
.Lgs_nl_2:
	s_mov_b64 vcc, exec
	s_and_saveexec_b64 s[0:1], vcc
	s_xor_b64 s[0:1], exec, s[0:1]
	s_cbranch_execz .LBB0_289
	v_add_u32_e32 v1, 1, v1
	v_mul_lo_u32 v1, v1, v0
	flat_load_dword v0, v[2:3] sc1
	s_waitcnt vmcnt(0) lgkmcnt(0)
	v_cmp_lt_u32_e32 vcc, v0, v1
	s_and_saveexec_b64 s[2:3], vcc
	s_cbranch_execz .LBB0_288
	s_add_u32 s6, s44, 0x600200
	s_addc_u32 s7, s62, 0
	s_mov_b32 s24, 1
	s_mov_b64 s[8:9], 0
	s_branch .LBB0_280

.LBB0_284:
	s_andn2_b64 s[12:13], s[12:13], exec
	s_and_b64 s[18:19], s[18:19], exec
	s_or_b64 s[12:13], s[12:13], s[18:19]
	s_and_saveexec_b64 s[18:19], s[16:17]
	s_cbranch_execz .LBB0_279
	v_mov_b64_e32 v[2:3], s[4:5]
	flat_load_dword v0, v[2:3] sc1
	s_add_i32 s24, s24, 1
	s_or_b64 s[12:13], s[12:13], exec
	s_waitcnt vmcnt(0) lgkmcnt(0)
	v_cmp_ge_u32_e32 vcc, v0, v1
	s_orn2_b64 s[14:15], vcc, exec
	s_branch .LBB0_279

.LBB0_375:
	s_lshl_b32 s0, s62, 8
	s_add_u32 s0, s43, s0
	s_addc_u32 s1, s44, 0
	v_mov_b32_e32 v1, s0
	v_add_co_u32_e32 v4, vcc, 0x601000, v1
	v_mov_b32_e32 v1, s1
	s_nop 0
	v_addc_co_u32_e32 v5, vcc, 0, v1, vcc
	flat_atomic_add v3, v[4:5], v219 offset:1024 sc0
	v_cvt_f32_u32_e32 v1, v2
	v_sub_u32_e32 v4, 0, v2
	s_add_u32 s23, s0, 0x600000
	s_addc_u32 s22, s1, 0
	v_rcp_iflag_f32_e32 v1, v1
	s_nop 0
	v_mul_f32_e32 v1, 0x4f7ffffe, v1
	v_cvt_u32_f32_e32 v1, v1
	v_mul_lo_u32 v4, v4, v1
	v_mul_hi_u32 v4, v1, v4
	v_add_u32_e32 v1, v1, v4
	s_waitcnt vmcnt(0) lgkmcnt(0)
	v_mul_hi_u32 v1, v3, v1
	v_mul_lo_u32 v4, v1, v2
	v_sub_u32_e32 v4, v3, v4
	v_cmp_ge_u32_e32 vcc, v4, v2
	v_add_u32_e32 v5, 1, v1
	s_nop 0
	v_cndmask_b32_e32 v1, v1, v5, vcc
	v_sub_u32_e32 v5, v4, v2
	v_cndmask_b32_e32 v4, v4, v5, vcc
	v_cmp_ge_u32_e32 vcc, v4, v2
	v_add_u32_e32 v4, 1, v1
	s_nop 0
	v_cndmask_b32_e32 v1, v1, v4, vcc
	v_add_u32_e32 v4, 1, v3
	v_mad_u64_u32 v[2:3], s[0:1], v2, v1, v[2:3]
	s_add_u32 s4, s43, 0x603400
	s_addc_u32 s5, s44, 0
	v_cmp_eq_u32_e32 vcc, v4, v2
	v_mov_b64_e32 v[2:3], s[4:5]
	v_mov_b32_e32 v4, 1
	s_cbranch_vccz .Lgs_nl_3
	buffer_wbl2 sc1
	s_waitcnt vmcnt(0)
	flat_atomic_add v[2:3], v4
.Lgs_nl_3:
	s_mov_b64 vcc, exec
	s_and_saveexec_b64 s[0:1], vcc
	s_xor_b64 s[0:1], exec, s[0:1]
	s_cbranch_execz .LBB0_388
	v_add_u32_e32 v1, 1, v1
	v_mul_lo_u32 v1, v1, v0
	flat_load_dword v0, v[2:3] sc1
	s_waitcnt vmcnt(0) lgkmcnt(0)
	v_cmp_lt_u32_e32 vcc, v0, v1
	s_and_saveexec_b64 s[2:3], vcc
	s_cbranch_execz .LBB0_387
	s_add_u32 s6, s43, 0x600200
	s_addc_u32 s7, s44, 0
	s_mov_b32 s24, 1
	s_mov_b64 s[8:9], 0
	s_branch .LBB0_379

.LBB0_662:
	s_lshl_b32 s0, s43, 8
	s_add_u32 s0, s37, s0
	s_addc_u32 s1, s42, 0
	v_mov_b32_e32 v1, s0
	v_add_co_u32_e32 v4, vcc, 0x601000, v1
	v_mov_b32_e32 v1, s1
	s_nop 0
	v_addc_co_u32_e32 v5, vcc, 0, v1, vcc
	flat_atomic_add v3, v[4:5], v219 offset:1024 sc0
	v_cvt_f32_u32_e32 v1, v2
	v_sub_u32_e32 v4, 0, v2
	s_add_u32 s23, s0, 0x600000
	s_addc_u32 s22, s1, 0
	v_rcp_iflag_f32_e32 v1, v1
	s_nop 0
	v_mul_f32_e32 v1, 0x4f7ffffe, v1
	v_cvt_u32_f32_e32 v1, v1
	v_mul_lo_u32 v4, v4, v1
	v_mul_hi_u32 v4, v1, v4
	v_add_u32_e32 v1, v1, v4
	s_waitcnt vmcnt(0) lgkmcnt(0)
	v_mul_hi_u32 v1, v3, v1
	v_mul_lo_u32 v4, v1, v2
	v_sub_u32_e32 v4, v3, v4
	v_cmp_ge_u32_e32 vcc, v4, v2
	v_add_u32_e32 v5, 1, v1
	s_nop 0
	v_cndmask_b32_e32 v1, v1, v5, vcc
	v_sub_u32_e32 v5, v4, v2
	v_cndmask_b32_e32 v4, v4, v5, vcc
	v_cmp_ge_u32_e32 vcc, v4, v2
	v_add_u32_e32 v4, 1, v1
	s_nop 0
	v_cndmask_b32_e32 v1, v1, v4, vcc
	v_add_u32_e32 v4, 1, v3
	v_mad_u64_u32 v[2:3], s[0:1], v2, v1, v[2:3]
	s_add_u32 s4, s37, 0x603400
	s_addc_u32 s5, s42, 0
	v_cmp_eq_u32_e32 vcc, v4, v2
	v_mov_b64_e32 v[2:3], s[4:5]
	v_mov_b32_e32 v4, 1
	s_cbranch_vccz .Lgs_nl_7
	buffer_wbl2 sc1
	s_waitcnt vmcnt(0)
	flat_atomic_add v[2:3], v4
.Lgs_nl_7:
	s_mov_b64 vcc, exec
	s_and_saveexec_b64 s[0:1], vcc
	s_xor_b64 s[0:1], exec, s[0:1]
	s_cbranch_execz .LBB0_675
	v_add_u32_e32 v1, 1, v1
	v_mul_lo_u32 v1, v1, v0
	flat_load_dword v0, v[2:3] sc1
	s_waitcnt vmcnt(0) lgkmcnt(0)
	v_cmp_lt_u32_e32 vcc, v0, v1
	s_and_saveexec_b64 s[2:3], vcc
	s_cbranch_execz .LBB0_674
	s_add_u32 s6, s37, 0x600200
	s_addc_u32 s7, s42, 0
	s_mov_b32 s24, 1
	s_mov_b64 s[8:9], 0
	s_branch .LBB0_666

.LBB0_1305:
	s_lshl_b32 s0, s62, 8
	s_add_u32 s0, s37, s0
	s_addc_u32 s1, s44, 0
	v_mov_b32_e32 v1, s0
	v_add_co_u32_e32 v4, vcc, 0x601000, v1
	v_mov_b32_e32 v1, s1
	s_nop 0
	v_addc_co_u32_e32 v5, vcc, 0, v1, vcc
	flat_atomic_add v3, v[4:5], v219 offset:1024 sc0
	v_cvt_f32_u32_e32 v1, v2
	v_sub_u32_e32 v4, 0, v2
	s_add_u32 s23, s0, 0x600000
	s_addc_u32 s22, s1, 0
	v_rcp_iflag_f32_e32 v1, v1
	s_nop 0
	v_mul_f32_e32 v1, 0x4f7ffffe, v1
	v_cvt_u32_f32_e32 v1, v1
	v_mul_lo_u32 v4, v4, v1
	v_mul_hi_u32 v4, v1, v4
	v_add_u32_e32 v1, v1, v4
	s_waitcnt vmcnt(0) lgkmcnt(0)
	v_mul_hi_u32 v1, v3, v1
	v_mul_lo_u32 v4, v1, v2
	v_sub_u32_e32 v4, v3, v4
	v_cmp_ge_u32_e32 vcc, v4, v2
	v_add_u32_e32 v5, 1, v1
	s_nop 0
	v_cndmask_b32_e32 v1, v1, v5, vcc
	v_sub_u32_e32 v5, v4, v2
	v_cndmask_b32_e32 v4, v4, v5, vcc
	v_cmp_ge_u32_e32 vcc, v4, v2
	v_add_u32_e32 v4, 1, v1
	s_nop 0
	v_cndmask_b32_e32 v1, v1, v4, vcc
	v_add_u32_e32 v4, 1, v3
	v_mad_u64_u32 v[2:3], s[0:1], v2, v1, v[2:3]
	s_add_u32 s4, s37, 0x603400
	s_addc_u32 s5, s44, 0
	v_cmp_eq_u32_e32 vcc, v4, v2
	v_mov_b64_e32 v[2:3], s[4:5]
	v_mov_b32_e32 v4, 1
	s_cbranch_vccz .Lgs_nl_9
	buffer_wbl2 sc1
	s_waitcnt vmcnt(0)
	flat_atomic_add v[2:3], v4
.Lgs_nl_9:
	s_mov_b64 vcc, exec
	s_and_saveexec_b64 s[0:1], vcc
	s_xor_b64 s[0:1], exec, s[0:1]
	s_cbranch_execz .LBB0_1318
	v_add_u32_e32 v1, 1, v1
	v_mul_lo_u32 v1, v1, v0
	flat_load_dword v0, v[2:3] sc1
	s_waitcnt vmcnt(0) lgkmcnt(0)
	v_cmp_lt_u32_e32 vcc, v0, v1
	s_and_saveexec_b64 s[2:3], vcc
	s_cbranch_execz .LBB0_1317
	s_add_u32 s6, s37, 0x600200
	s_addc_u32 s7, s44, 0
	s_mov_b32 s24, 1
	s_mov_b64 s[8:9], 0
	s_branch .LBB0_1309
